# residual GEMM epilogue rewritten: accumulators transposed through a private LDS area so each wave access covers whole 128-byte row segments
# speedup vs baseline: 1.0385x; 1.0321x over previous
.LBB0_540:
	s_andn2_b64 vcc, exec, s[10:11]
	s_cbranch_vccnz .LBB0_514
	v_mbcnt_lo_u32_b32 v141, -1, 0
	v_mbcnt_hi_u32_b32 v141, -1, v141
	s_lshl_b32 s72, s81, 1
	s_add_i32 s72, s72, 0x20000
	s_cmp_eq_u32 s81, 0x1c00
	s_cselect_b32 s99, 0x800, 0
	s_add_i32 s72, s72, s99
	v_and_b32_e32 v132, 15, v141
	v_lshrrev_b32_e32 v133, 4, v141
	v_bfe_u32 v134, v141, 1, 3
	v_xor_b32_e32 v133, v133, v134
	v_lshlrev_b32_e32 v133, 4, v133
	v_lshl_add_u32 v132, v132, 7, v133
	v_add_u32_e32 v132, s72, v132
	v_xor_b32_e32 v133, 64, v132
	v_lshrrev_b32_e32 v134, 3, v141
	v_and_b32_e32 v135, 7, v141
	v_lshrrev_b32_e32 v148, 4, v141
	v_xor_b32_e32 v135, v135, v148
	v_lshlrev_b32_e32 v135, 4, v135
	v_lshl_add_u32 v134, v134, 7, v135
	v_add_u32_e32 v134, s72, v134
	v_xor_b32_e32 v135, 64, v134
	v_and_b32_e32 v148, 64, v151
	v_lshrrev_b32_e32 v140, 3, v141
	v_add_u32_e32 v140, v148, v140
	v_and_b32_e32 v148, 7, v141
	s_lshl_b32 s99, s23, 7
	v_lshlrev_b32_e32 v136, 4, v148
	v_lshl_add_u32 v136, v140, 12, v136
	v_add_u32_e32 v136, s99, v136
	v_add_u32_e32 v137, 0x8000, v136
	v_mov_b32_e32 v173, v136
	v_mov_b32_e32 v177, v137
	s_lshl_b32 s99, s23, 6
	v_lshlrev_b32_e32 v138, 3, v148
	v_lshl_add_u32 v138, v140, 11, v138
	v_add_u32_e32 v138, s99, v138
	v_add_u32_e32 v139, 0x4000, v138
	v_lshlrev_b32_e32 v140, 6, v140
	s_lshl_b32 s99, s20, 20
	s_lshl_b32 s72, s25, 10
	s_add_u32 s99, s99, s72
	s_add_u32 s84, s16, s99
	s_addc_u32 s85, s17, 0
	s_lshl_b32 s99, s20, 19
	s_lshl_b32 s72, s25, 9
	s_add_u32 s99, s99, s72
	s_add_u32 s10, s70, s99
	s_addc_u32 s11, s71, 0
	s_lshl_b32 s99, s20, 14
	s_lshl_b32 s72, s25, 2
	s_or_b32 s72, s72, s23
	s_lshl_b32 s72, s72, 2
	s_add_u32 s99, s99, s72
	s_add_u32 s78, s38, s99
	s_addc_u32 s79, s39, 0
	s_mov_b32 s100, 0x1010101
	global_load_dwordx4 v[190:193], v136, s[84:85] nt
	global_load_dwordx4 v[194:197], v136, s[84:85] offset:512 nt
	global_load_dwordx4 v[198:201], v137, s[84:85] nt
	global_load_dwordx4 v[202:205], v137, s[84:85] offset:512 nt
	v_add_u32_e32 v136, 0x10000, v136
	v_add_u32_e32 v137, 0x10000, v137
	global_load_dwordx4 v[206:209], v136, s[84:85] nt
	global_load_dwordx4 v[210:213], v136, s[84:85] offset:512 nt
	global_load_dwordx4 v[214:217], v137, s[84:85] nt
	global_load_dwordx4 v[218:221], v137, s[84:85] offset:512 nt
	v_add_u32_e32 v136, 0x10000, v136
	v_add_u32_e32 v137, 0x10000, v137
	global_load_dwordx4 v[222:225], v136, s[84:85] nt
	global_load_dwordx4 v[226:229], v136, s[84:85] offset:512 nt
	global_load_dwordx4 v[230:233], v137, s[84:85] nt
	global_load_dwordx4 v[128:131], v137, s[84:85] offset:512 nt
	v_add_u32_e32 v136, 0x10000, v136
	v_add_u32_e32 v137, 0x10000, v137
	ds_write_b128 v132, v[124:127]
	ds_write_b128 v133, v[116:119]
	ds_read_b128 v[124:127], v134
	ds_read_b128 v[116:119], v135 offset:1024
	ds_write_b128 v132, v[108:111]
	ds_write_b128 v133, v[100:103]
	ds_read_b128 v[108:111], v134
	ds_read_b128 v[100:103], v135 offset:1024
	ds_write_b128 v132, v[120:123]
	ds_write_b128 v133, v[112:115]
	ds_read_b128 v[120:123], v134
	ds_read_b128 v[112:115], v135 offset:1024
	ds_write_b128 v132, v[104:107]
	ds_write_b128 v133, v[96:99]
	ds_read_b128 v[104:107], v134
	ds_read_b128 v[96:99], v135 offset:1024
	ds_write_b128 v132, v[92:95]
	ds_write_b128 v133, v[84:87]
	ds_read_b128 v[92:95], v134
	ds_read_b128 v[84:87], v135 offset:1024
	ds_write_b128 v132, v[76:79]
	ds_write_b128 v133, v[68:71]
	ds_read_b128 v[76:79], v134
	ds_read_b128 v[68:71], v135 offset:1024
	ds_write_b128 v132, v[88:91]
	ds_write_b128 v133, v[80:83]
	ds_read_b128 v[88:91], v134
	ds_read_b128 v[80:83], v135 offset:1024
	ds_write_b128 v132, v[72:75]
	ds_write_b128 v133, v[64:67]
	ds_read_b128 v[72:75], v134
	ds_read_b128 v[64:67], v135 offset:1024
	ds_write_b128 v132, v[60:63]
	ds_write_b128 v133, v[56:59]
	ds_read_b128 v[60:63], v134
	ds_read_b128 v[56:59], v135 offset:1024
	ds_write_b128 v132, v[44:47]
	ds_write_b128 v133, v[36:39]
	ds_read_b128 v[44:47], v134
	ds_read_b128 v[36:39], v135 offset:1024
	ds_write_b128 v132, v[52:55]
	ds_write_b128 v133, v[48:51]
	ds_read_b128 v[52:55], v134
	ds_read_b128 v[48:51], v135 offset:1024
	ds_write_b128 v132, v[40:43]
	ds_write_b128 v133, v[32:35]
	ds_read_b128 v[40:43], v134
	ds_read_b128 v[32:35], v135 offset:1024
	ds_write_b128 v132, v[28:31]
	ds_write_b128 v133, v[20:23]
	ds_read_b128 v[28:31], v134
	ds_read_b128 v[20:23], v135 offset:1024
	ds_write_b128 v132, v[12:15]
	ds_write_b128 v133, v[4:7]
	ds_read_b128 v[12:15], v134
	ds_read_b128 v[4:7], v135 offset:1024
	ds_write_b128 v132, v[24:27]
	ds_write_b128 v133, v[16:19]
	ds_read_b128 v[24:27], v134
	ds_read_b128 v[16:19], v135 offset:1024
	ds_write_b128 v132, v[8:11]
	ds_write_b128 v133, v[0:3]
	ds_read_b128 v[8:11], v134
	ds_read_b128 v[0:3], v135 offset:1024
	s_waitcnt lgkmcnt(0)
	s_waitcnt vmcnt(8)
	v_pk_fma_f32 v[124:125], s[82:83], v[124:125], v[190:191]
	v_pk_fma_f32 v[126:127], s[82:83], v[126:127], v[192:193]
	v_pk_fma_f32 v[108:109], s[82:83], v[108:109], v[194:195]
	v_pk_fma_f32 v[110:111], s[82:83], v[110:111], v[196:197]
	v_pk_fma_f32 v[116:117], s[82:83], v[116:117], v[198:199]
	v_pk_fma_f32 v[118:119], s[82:83], v[118:119], v[200:201]
	v_pk_fma_f32 v[100:101], s[82:83], v[100:101], v[202:203]
	v_pk_fma_f32 v[102:103], s[82:83], v[102:103], v[204:205]
	global_store_dwordx4 v173, v[124:127], s[84:85] nt
	v_cvt_pk_bf16_f32 v164, v124, v125
	v_cvt_pk_bf16_f32 v165, v126, v127
	v_mul_f32_e32 v132, v124, v124
	v_fmac_f32_e32 v132, v125, v125
	v_fmac_f32_e32 v132, v126, v126
	v_fmac_f32_e32 v132, v127, v127
	global_store_dwordx2 v138, v[164:165], s[10:11]
	global_store_dwordx4 v173, v[108:111], s[84:85] offset:512 nt
	v_cvt_pk_bf16_f32 v166, v108, v109
	v_cvt_pk_bf16_f32 v167, v110, v111
	v_fmac_f32_e32 v132, v108, v108
	v_fmac_f32_e32 v132, v109, v109
	v_fmac_f32_e32 v132, v110, v110
	v_fmac_f32_e32 v132, v111, v111
	global_store_dwordx2 v138, v[166:167], s[10:11] offset:256
	global_store_dwordx4 v177, v[116:119], s[84:85] nt
	v_cvt_pk_bf16_f32 v174, v116, v117
	v_cvt_pk_bf16_f32 v175, v118, v119
	v_mul_f32_e32 v133, v116, v116
	v_fmac_f32_e32 v133, v117, v117
	v_fmac_f32_e32 v133, v118, v118
	v_fmac_f32_e32 v133, v119, v119
	global_store_dwordx2 v139, v[174:175], s[10:11]
	global_store_dwordx4 v177, v[100:103], s[84:85] offset:512 nt
	v_cvt_pk_bf16_f32 v142, v100, v101
	v_cvt_pk_bf16_f32 v143, v102, v103
	v_fmac_f32_e32 v133, v100, v100
	v_fmac_f32_e32 v133, v101, v101
	v_fmac_f32_e32 v133, v102, v102
	v_fmac_f32_e32 v133, v103, v103
	global_store_dwordx2 v139, v[142:143], s[10:11] offset:256
	s_nop 1
	v_add_f32_dpp v132, v132, v132 quad_perm:[1,0,3,2] row_mask:0xf bank_mask:0xf
	v_add_f32_dpp v133, v133, v133 quad_perm:[1,0,3,2] row_mask:0xf bank_mask:0xf
	s_nop 0
	v_add_f32_dpp v132, v132, v132 quad_perm:[2,3,0,1] row_mask:0xf bank_mask:0xf
	v_add_f32_dpp v133, v133, v133 quad_perm:[2,3,0,1] row_mask:0xf bank_mask:0xf
	s_nop 0
	v_add_f32_dpp v132, v132, v132 row_half_mirror row_mask:0xf bank_mask:0xf
	v_add_f32_dpp v133, v133, v133 row_half_mirror row_mask:0xf bank_mask:0xf
	s_nop 0
	s_mov_b32 exec_lo, s100
	s_mov_b32 exec_hi, s100
	global_store_dword v140, v132, s[78:79]
	global_store_dword v140, v133, s[78:79] offset:512
	s_mov_b64 exec, -1
	v_add_u32_e32 v173, 0x10000, v173
	v_add_u32_e32 v177, 0x10000, v177
	v_add_u32_e32 v138, 0x8000, v138
	v_add_u32_e32 v139, 0x8000, v139
	global_load_dwordx4 v[190:193], v136, s[84:85] nt
	global_load_dwordx4 v[194:197], v136, s[84:85] offset:512 nt
	global_load_dwordx4 v[198:201], v137, s[84:85] nt
	global_load_dwordx4 v[202:205], v137, s[84:85] offset:512 nt
	v_add_u32_e32 v136, 0x50000, v136
	v_add_u32_e32 v137, 0x50000, v137
	s_waitcnt vmcnt(18)
	v_pk_fma_f32 v[120:121], s[82:83], v[120:121], v[206:207]
	v_pk_fma_f32 v[122:123], s[82:83], v[122:123], v[208:209]
	v_pk_fma_f32 v[104:105], s[82:83], v[104:105], v[210:211]
	v_pk_fma_f32 v[106:107], s[82:83], v[106:107], v[212:213]
	v_pk_fma_f32 v[112:113], s[82:83], v[112:113], v[214:215]
	v_pk_fma_f32 v[114:115], s[82:83], v[114:115], v[216:217]
	v_pk_fma_f32 v[96:97], s[82:83], v[96:97], v[218:219]
	v_pk_fma_f32 v[98:99], s[82:83], v[98:99], v[220:221]
	global_store_dwordx4 v173, v[120:123], s[84:85] nt
	v_cvt_pk_bf16_f32 v164, v120, v121
	v_cvt_pk_bf16_f32 v165, v122, v123
	v_mul_f32_e32 v134, v120, v120
	v_fmac_f32_e32 v134, v121, v121
	v_fmac_f32_e32 v134, v122, v122
	v_fmac_f32_e32 v134, v123, v123
	global_store_dwordx2 v138, v[164:165], s[10:11]
	global_store_dwordx4 v173, v[104:107], s[84:85] offset:512 nt
	v_cvt_pk_bf16_f32 v166, v104, v105
	v_cvt_pk_bf16_f32 v167, v106, v107
	v_fmac_f32_e32 v134, v104, v104
	v_fmac_f32_e32 v134, v105, v105
	v_fmac_f32_e32 v134, v106, v106
	v_fmac_f32_e32 v134, v107, v107
	global_store_dwordx2 v138, v[166:167], s[10:11] offset:256
	global_store_dwordx4 v177, v[112:115], s[84:85] nt
	v_cvt_pk_bf16_f32 v174, v112, v113
	v_cvt_pk_bf16_f32 v175, v114, v115
	v_mul_f32_e32 v135, v112, v112
	v_fmac_f32_e32 v135, v113, v113
	v_fmac_f32_e32 v135, v114, v114
	v_fmac_f32_e32 v135, v115, v115
	global_store_dwordx2 v139, v[174:175], s[10:11]
	global_store_dwordx4 v177, v[96:99], s[84:85] offset:512 nt
	v_cvt_pk_bf16_f32 v142, v96, v97
	v_cvt_pk_bf16_f32 v143, v98, v99
	v_fmac_f32_e32 v135, v96, v96
	v_fmac_f32_e32 v135, v97, v97
	v_fmac_f32_e32 v135, v98, v98
	v_fmac_f32_e32 v135, v99, v99
	global_store_dwordx2 v139, v[142:143], s[10:11] offset:256
	s_nop 1
	v_add_f32_dpp v134, v134, v134 quad_perm:[1,0,3,2] row_mask:0xf bank_mask:0xf
	v_add_f32_dpp v135, v135, v135 quad_perm:[1,0,3,2] row_mask:0xf bank_mask:0xf
	s_nop 0
	v_add_f32_dpp v134, v134, v134 quad_perm:[2,3,0,1] row_mask:0xf bank_mask:0xf
	v_add_f32_dpp v135, v135, v135 quad_perm:[2,3,0,1] row_mask:0xf bank_mask:0xf
	s_nop 0
	v_add_f32_dpp v134, v134, v134 row_half_mirror row_mask:0xf bank_mask:0xf
	v_add_f32_dpp v135, v135, v135 row_half_mirror row_mask:0xf bank_mask:0xf
	s_nop 0
	s_mov_b32 exec_lo, s100
	s_mov_b32 exec_hi, s100
	global_store_dword v140, v134, s[78:79] offset:1024
	global_store_dword v140, v135, s[78:79] offset:1536
	s_mov_b64 exec, -1
	v_add_u32_e32 v173, 0x10000, v173
	v_add_u32_e32 v177, 0x10000, v177
	v_add_u32_e32 v138, 0x8000, v138
	v_add_u32_e32 v139, 0x8000, v139
	global_load_dwordx4 v[206:209], v136, s[84:85] nt
	global_load_dwordx4 v[210:213], v136, s[84:85] offset:512 nt
	global_load_dwordx4 v[214:217], v137, s[84:85] nt
	global_load_dwordx4 v[218:221], v137, s[84:85] offset:512 nt
	v_add_u32_e32 v136, 0x10000, v136
	v_add_u32_e32 v137, 0x10000, v137
	s_waitcnt vmcnt(28)
	v_pk_fma_f32 v[92:93], s[82:83], v[92:93], v[222:223]
	v_pk_fma_f32 v[94:95], s[82:83], v[94:95], v[224:225]
	v_pk_fma_f32 v[76:77], s[82:83], v[76:77], v[226:227]
	v_pk_fma_f32 v[78:79], s[82:83], v[78:79], v[228:229]
	v_pk_fma_f32 v[84:85], s[82:83], v[84:85], v[230:231]
	v_pk_fma_f32 v[86:87], s[82:83], v[86:87], v[232:233]
	v_pk_fma_f32 v[68:69], s[82:83], v[68:69], v[128:129]
	v_pk_fma_f32 v[70:71], s[82:83], v[70:71], v[130:131]
	global_store_dwordx4 v173, v[92:95], s[84:85] nt
	v_cvt_pk_bf16_f32 v164, v92, v93
	v_cvt_pk_bf16_f32 v165, v94, v95
	v_mul_f32_e32 v132, v92, v92
	v_fmac_f32_e32 v132, v93, v93
	v_fmac_f32_e32 v132, v94, v94
	v_fmac_f32_e32 v132, v95, v95
	global_store_dwordx2 v138, v[164:165], s[10:11]
	global_store_dwordx4 v173, v[76:79], s[84:85] offset:512 nt
	v_cvt_pk_bf16_f32 v166, v76, v77
	v_cvt_pk_bf16_f32 v167, v78, v79
	v_fmac_f32_e32 v132, v76, v76
	v_fmac_f32_e32 v132, v77, v77
	v_fmac_f32_e32 v132, v78, v78
	v_fmac_f32_e32 v132, v79, v79
	global_store_dwordx2 v138, v[166:167], s[10:11] offset:256
	global_store_dwordx4 v177, v[84:87], s[84:85] nt
	v_cvt_pk_bf16_f32 v174, v84, v85
	v_cvt_pk_bf16_f32 v175, v86, v87
	v_mul_f32_e32 v133, v84, v84
	v_fmac_f32_e32 v133, v85, v85
	v_fmac_f32_e32 v133, v86, v86
	v_fmac_f32_e32 v133, v87, v87
	global_store_dwordx2 v139, v[174:175], s[10:11]
	global_store_dwordx4 v177, v[68:71], s[84:85] offset:512 nt
	v_cvt_pk_bf16_f32 v142, v68, v69
	v_cvt_pk_bf16_f32 v143, v70, v71
	v_fmac_f32_e32 v133, v68, v68
	v_fmac_f32_e32 v133, v69, v69
	v_fmac_f32_e32 v133, v70, v70
	v_fmac_f32_e32 v133, v71, v71
	global_store_dwordx2 v139, v[142:143], s[10:11] offset:256
	s_nop 1
	v_add_f32_dpp v132, v132, v132 quad_perm:[1,0,3,2] row_mask:0xf bank_mask:0xf
	v_add_f32_dpp v133, v133, v133 quad_perm:[1,0,3,2] row_mask:0xf bank_mask:0xf
	s_nop 0
	v_add_f32_dpp v132, v132, v132 quad_perm:[2,3,0,1] row_mask:0xf bank_mask:0xf
	v_add_f32_dpp v133, v133, v133 quad_perm:[2,3,0,1] row_mask:0xf bank_mask:0xf
	s_nop 0
	v_add_f32_dpp v132, v132, v132 row_half_mirror row_mask:0xf bank_mask:0xf
	v_add_f32_dpp v133, v133, v133 row_half_mirror row_mask:0xf bank_mask:0xf
	s_nop 0
	s_mov_b32 exec_lo, s100
	s_mov_b32 exec_hi, s100
	global_store_dword v140, v132, s[78:79] offset:2048
	global_store_dword v140, v133, s[78:79] offset:2560
	s_mov_b64 exec, -1
	v_add_u32_e32 v173, 0x10000, v173
	v_add_u32_e32 v177, 0x10000, v177
	v_add_u32_e32 v138, 0x8000, v138
	v_add_u32_e32 v139, 0x8000, v139
	global_load_dwordx4 v[222:225], v136, s[84:85] nt
	global_load_dwordx4 v[226:229], v136, s[84:85] offset:512 nt
	global_load_dwordx4 v[230:233], v137, s[84:85] nt
	global_load_dwordx4 v[128:131], v137, s[84:85] offset:512 nt
	v_add_u32_e32 v136, 0x10000, v136
	v_add_u32_e32 v137, 0x10000, v137
	s_waitcnt vmcnt(28)
	v_pk_fma_f32 v[88:89], s[82:83], v[88:89], v[190:191]
	v_pk_fma_f32 v[90:91], s[82:83], v[90:91], v[192:193]
	v_pk_fma_f32 v[72:73], s[82:83], v[72:73], v[194:195]
	v_pk_fma_f32 v[74:75], s[82:83], v[74:75], v[196:197]
	v_pk_fma_f32 v[80:81], s[82:83], v[80:81], v[198:199]
	v_pk_fma_f32 v[82:83], s[82:83], v[82:83], v[200:201]
	v_pk_fma_f32 v[64:65], s[82:83], v[64:65], v[202:203]
	v_pk_fma_f32 v[66:67], s[82:83], v[66:67], v[204:205]
	global_store_dwordx4 v173, v[88:91], s[84:85] nt
	v_cvt_pk_bf16_f32 v164, v88, v89
	v_cvt_pk_bf16_f32 v165, v90, v91
	v_mul_f32_e32 v134, v88, v88
	v_fmac_f32_e32 v134, v89, v89
	v_fmac_f32_e32 v134, v90, v90
	v_fmac_f32_e32 v134, v91, v91
	global_store_dwordx2 v138, v[164:165], s[10:11]
	global_store_dwordx4 v173, v[72:75], s[84:85] offset:512 nt
	v_cvt_pk_bf16_f32 v166, v72, v73
	v_cvt_pk_bf16_f32 v167, v74, v75
	v_fmac_f32_e32 v134, v72, v72
	v_fmac_f32_e32 v134, v73, v73
	v_fmac_f32_e32 v134, v74, v74
	v_fmac_f32_e32 v134, v75, v75
	global_store_dwordx2 v138, v[166:167], s[10:11] offset:256
	global_store_dwordx4 v177, v[80:83], s[84:85] nt
	v_cvt_pk_bf16_f32 v174, v80, v81
	v_cvt_pk_bf16_f32 v175, v82, v83
	v_mul_f32_e32 v135, v80, v80
	v_fmac_f32_e32 v135, v81, v81
	v_fmac_f32_e32 v135, v82, v82
	v_fmac_f32_e32 v135, v83, v83
	global_store_dwordx2 v139, v[174:175], s[10:11]
	global_store_dwordx4 v177, v[64:67], s[84:85] offset:512 nt
	v_cvt_pk_bf16_f32 v142, v64, v65
	v_cvt_pk_bf16_f32 v143, v66, v67
	v_fmac_f32_e32 v135, v64, v64
	v_fmac_f32_e32 v135, v65, v65
	v_fmac_f32_e32 v135, v66, v66
	v_fmac_f32_e32 v135, v67, v67
	global_store_dwordx2 v139, v[142:143], s[10:11] offset:256
	s_nop 1
	v_add_f32_dpp v134, v134, v134 quad_perm:[1,0,3,2] row_mask:0xf bank_mask:0xf
	v_add_f32_dpp v135, v135, v135 quad_perm:[1,0,3,2] row_mask:0xf bank_mask:0xf
	s_nop 0
	v_add_f32_dpp v134, v134, v134 quad_perm:[2,3,0,1] row_mask:0xf bank_mask:0xf
	v_add_f32_dpp v135, v135, v135 quad_perm:[2,3,0,1] row_mask:0xf bank_mask:0xf
	s_nop 0
	v_add_f32_dpp v134, v134, v134 row_half_mirror row_mask:0xf bank_mask:0xf
	v_add_f32_dpp v135, v135, v135 row_half_mirror row_mask:0xf bank_mask:0xf
	s_nop 0
	s_mov_b32 exec_lo, s100
	s_mov_b32 exec_hi, s100
	global_store_dword v140, v134, s[78:79] offset:3072
	global_store_dword v140, v135, s[78:79] offset:3584
	s_mov_b64 exec, -1
	v_add_u32_e32 v173, 0x50000, v173
	v_add_u32_e32 v177, 0x50000, v177
	v_add_u32_e32 v138, 0x28000, v138
	v_add_u32_e32 v139, 0x28000, v139
	s_add_u32 s78, s78, 0x2000
	s_addc_u32 s79, s79, 0
	global_load_dwordx4 v[190:193], v136, s[84:85] nt
	global_load_dwordx4 v[194:197], v136, s[84:85] offset:512 nt
	global_load_dwordx4 v[198:201], v137, s[84:85] nt
	global_load_dwordx4 v[202:205], v137, s[84:85] offset:512 nt
	v_add_u32_e32 v136, 0x10000, v136
	v_add_u32_e32 v137, 0x10000, v137
	s_waitcnt vmcnt(28)
	v_pk_fma_f32 v[60:61], s[82:83], v[60:61], v[206:207]
	v_pk_fma_f32 v[62:63], s[82:83], v[62:63], v[208:209]
	v_pk_fma_f32 v[44:45], s[82:83], v[44:45], v[210:211]
	v_pk_fma_f32 v[46:47], s[82:83], v[46:47], v[212:213]
	v_pk_fma_f32 v[56:57], s[82:83], v[56:57], v[214:215]
	v_pk_fma_f32 v[58:59], s[82:83], v[58:59], v[216:217]
	v_pk_fma_f32 v[36:37], s[82:83], v[36:37], v[218:219]
	v_pk_fma_f32 v[38:39], s[82:83], v[38:39], v[220:221]
	global_store_dwordx4 v173, v[60:63], s[84:85] nt
	v_cvt_pk_bf16_f32 v164, v60, v61
	v_cvt_pk_bf16_f32 v165, v62, v63
	v_mul_f32_e32 v132, v60, v60
	v_fmac_f32_e32 v132, v61, v61
	v_fmac_f32_e32 v132, v62, v62
	v_fmac_f32_e32 v132, v63, v63
	global_store_dwordx2 v138, v[164:165], s[10:11]
	global_store_dwordx4 v173, v[44:47], s[84:85] offset:512 nt
	v_cvt_pk_bf16_f32 v166, v44, v45
	v_cvt_pk_bf16_f32 v167, v46, v47
	v_fmac_f32_e32 v132, v44, v44
	v_fmac_f32_e32 v132, v45, v45
	v_fmac_f32_e32 v132, v46, v46
	v_fmac_f32_e32 v132, v47, v47
	global_store_dwordx2 v138, v[166:167], s[10:11] offset:256
	global_store_dwordx4 v177, v[56:59], s[84:85] nt
	v_cvt_pk_bf16_f32 v174, v56, v57
	v_cvt_pk_bf16_f32 v175, v58, v59
	v_mul_f32_e32 v133, v56, v56
	v_fmac_f32_e32 v133, v57, v57
	v_fmac_f32_e32 v133, v58, v58
	v_fmac_f32_e32 v133, v59, v59
	global_store_dwordx2 v139, v[174:175], s[10:11]
	global_store_dwordx4 v177, v[36:39], s[84:85] offset:512 nt
	v_cvt_pk_bf16_f32 v142, v36, v37
	v_cvt_pk_bf16_f32 v143, v38, v39
	v_fmac_f32_e32 v133, v36, v36
	v_fmac_f32_e32 v133, v37, v37
	v_fmac_f32_e32 v133, v38, v38
	v_fmac_f32_e32 v133, v39, v39
	global_store_dwordx2 v139, v[142:143], s[10:11] offset:256
	s_nop 1
	v_add_f32_dpp v132, v132, v132 quad_perm:[1,0,3,2] row_mask:0xf bank_mask:0xf
	v_add_f32_dpp v133, v133, v133 quad_perm:[1,0,3,2] row_mask:0xf bank_mask:0xf
	s_nop 0
	v_add_f32_dpp v132, v132, v132 quad_perm:[2,3,0,1] row_mask:0xf bank_mask:0xf
	v_add_f32_dpp v133, v133, v133 quad_perm:[2,3,0,1] row_mask:0xf bank_mask:0xf
	s_nop 0
	v_add_f32_dpp v132, v132, v132 row_half_mirror row_mask:0xf bank_mask:0xf
	v_add_f32_dpp v133, v133, v133 row_half_mirror row_mask:0xf bank_mask:0xf
	s_nop 0
	s_mov_b32 exec_lo, s100
	s_mov_b32 exec_hi, s100
	global_store_dword v140, v132, s[78:79]
	global_store_dword v140, v133, s[78:79] offset:512
	s_mov_b64 exec, -1
	v_add_u32_e32 v173, 0x10000, v173
	v_add_u32_e32 v177, 0x10000, v177
	v_add_u32_e32 v138, 0x8000, v138
	v_add_u32_e32 v139, 0x8000, v139
	global_load_dwordx4 v[206:209], v136, s[84:85] nt
	global_load_dwordx4 v[210:213], v136, s[84:85] offset:512 nt
	global_load_dwordx4 v[214:217], v137, s[84:85] nt
	global_load_dwordx4 v[218:221], v137, s[84:85] offset:512 nt
	s_waitcnt vmcnt(28)
	v_pk_fma_f32 v[52:53], s[82:83], v[52:53], v[222:223]
	v_pk_fma_f32 v[54:55], s[82:83], v[54:55], v[224:225]
	v_pk_fma_f32 v[40:41], s[82:83], v[40:41], v[226:227]
	v_pk_fma_f32 v[42:43], s[82:83], v[42:43], v[228:229]
	v_pk_fma_f32 v[48:49], s[82:83], v[48:49], v[230:231]
	v_pk_fma_f32 v[50:51], s[82:83], v[50:51], v[232:233]
	v_pk_fma_f32 v[32:33], s[82:83], v[32:33], v[128:129]
	v_pk_fma_f32 v[34:35], s[82:83], v[34:35], v[130:131]
	global_store_dwordx4 v173, v[52:55], s[84:85] nt
	v_cvt_pk_bf16_f32 v164, v52, v53
	v_cvt_pk_bf16_f32 v165, v54, v55
	v_mul_f32_e32 v134, v52, v52
	v_fmac_f32_e32 v134, v53, v53
	v_fmac_f32_e32 v134, v54, v54
	v_fmac_f32_e32 v134, v55, v55
	global_store_dwordx2 v138, v[164:165], s[10:11]
	global_store_dwordx4 v173, v[40:43], s[84:85] offset:512 nt
	v_cvt_pk_bf16_f32 v166, v40, v41
	v_cvt_pk_bf16_f32 v167, v42, v43
	v_fmac_f32_e32 v134, v40, v40
	v_fmac_f32_e32 v134, v41, v41
	v_fmac_f32_e32 v134, v42, v42
	v_fmac_f32_e32 v134, v43, v43
	global_store_dwordx2 v138, v[166:167], s[10:11] offset:256
	global_store_dwordx4 v177, v[48:51], s[84:85] nt
	v_cvt_pk_bf16_f32 v174, v48, v49
	v_cvt_pk_bf16_f32 v175, v50, v51
	v_mul_f32_e32 v135, v48, v48
	v_fmac_f32_e32 v135, v49, v49
	v_fmac_f32_e32 v135, v50, v50
	v_fmac_f32_e32 v135, v51, v51
	global_store_dwordx2 v139, v[174:175], s[10:11]
	global_store_dwordx4 v177, v[32:35], s[84:85] offset:512 nt
	v_cvt_pk_bf16_f32 v142, v32, v33
	v_cvt_pk_bf16_f32 v143, v34, v35
	v_fmac_f32_e32 v135, v32, v32
	v_fmac_f32_e32 v135, v33, v33
	v_fmac_f32_e32 v135, v34, v34
	v_fmac_f32_e32 v135, v35, v35
	global_store_dwordx2 v139, v[142:143], s[10:11] offset:256
	s_nop 1
	v_add_f32_dpp v134, v134, v134 quad_perm:[1,0,3,2] row_mask:0xf bank_mask:0xf
	v_add_f32_dpp v135, v135, v135 quad_perm:[1,0,3,2] row_mask:0xf bank_mask:0xf
	s_nop 0
	v_add_f32_dpp v134, v134, v134 quad_perm:[2,3,0,1] row_mask:0xf bank_mask:0xf
	v_add_f32_dpp v135, v135, v135 quad_perm:[2,3,0,1] row_mask:0xf bank_mask:0xf
	s_nop 0
	v_add_f32_dpp v134, v134, v134 row_half_mirror row_mask:0xf bank_mask:0xf
	v_add_f32_dpp v135, v135, v135 row_half_mirror row_mask:0xf bank_mask:0xf
	s_nop 0
	s_mov_b32 exec_lo, s100
	s_mov_b32 exec_hi, s100
	global_store_dword v140, v134, s[78:79] offset:1024
	global_store_dword v140, v135, s[78:79] offset:1536
	s_mov_b64 exec, -1
	v_add_u32_e32 v173, 0x10000, v173
	v_add_u32_e32 v177, 0x10000, v177
	v_add_u32_e32 v138, 0x8000, v138
	v_add_u32_e32 v139, 0x8000, v139
	s_waitcnt vmcnt(24)
	v_pk_fma_f32 v[28:29], s[82:83], v[28:29], v[190:191]
	v_pk_fma_f32 v[30:31], s[82:83], v[30:31], v[192:193]
	v_pk_fma_f32 v[12:13], s[82:83], v[12:13], v[194:195]
	v_pk_fma_f32 v[14:15], s[82:83], v[14:15], v[196:197]
	v_pk_fma_f32 v[20:21], s[82:83], v[20:21], v[198:199]
	v_pk_fma_f32 v[22:23], s[82:83], v[22:23], v[200:201]
	v_pk_fma_f32 v[4:5], s[82:83], v[4:5], v[202:203]
	v_pk_fma_f32 v[6:7], s[82:83], v[6:7], v[204:205]
	global_store_dwordx4 v173, v[28:31], s[84:85] nt
	v_cvt_pk_bf16_f32 v164, v28, v29
	v_cvt_pk_bf16_f32 v165, v30, v31
	v_mul_f32_e32 v132, v28, v28
	v_fmac_f32_e32 v132, v29, v29
	v_fmac_f32_e32 v132, v30, v30
	v_fmac_f32_e32 v132, v31, v31
	global_store_dwordx2 v138, v[164:165], s[10:11]
	global_store_dwordx4 v173, v[12:15], s[84:85] offset:512 nt
	v_cvt_pk_bf16_f32 v166, v12, v13
	v_cvt_pk_bf16_f32 v167, v14, v15
	v_fmac_f32_e32 v132, v12, v12
	v_fmac_f32_e32 v132, v13, v13
	v_fmac_f32_e32 v132, v14, v14
	v_fmac_f32_e32 v132, v15, v15
	global_store_dwordx2 v138, v[166:167], s[10:11] offset:256
	global_store_dwordx4 v177, v[20:23], s[84:85] nt
	v_cvt_pk_bf16_f32 v174, v20, v21
	v_cvt_pk_bf16_f32 v175, v22, v23
	v_mul_f32_e32 v133, v20, v20
	v_fmac_f32_e32 v133, v21, v21
	v_fmac_f32_e32 v133, v22, v22
	v_fmac_f32_e32 v133, v23, v23
	global_store_dwordx2 v139, v[174:175], s[10:11]
	global_store_dwordx4 v177, v[4:7], s[84:85] offset:512 nt
	v_cvt_pk_bf16_f32 v142, v4, v5
	v_cvt_pk_bf16_f32 v143, v6, v7
	v_fmac_f32_e32 v133, v4, v4
	v_fmac_f32_e32 v133, v5, v5
	v_fmac_f32_e32 v133, v6, v6
	v_fmac_f32_e32 v133, v7, v7
	global_store_dwordx2 v139, v[142:143], s[10:11] offset:256
	s_nop 1
	v_add_f32_dpp v132, v132, v132 quad_perm:[1,0,3,2] row_mask:0xf bank_mask:0xf
	v_add_f32_dpp v133, v133, v133 quad_perm:[1,0,3,2] row_mask:0xf bank_mask:0xf
	s_nop 0
	v_add_f32_dpp v132, v132, v132 quad_perm:[2,3,0,1] row_mask:0xf bank_mask:0xf
	v_add_f32_dpp v133, v133, v133 quad_perm:[2,3,0,1] row_mask:0xf bank_mask:0xf
	s_nop 0
	v_add_f32_dpp v132, v132, v132 row_half_mirror row_mask:0xf bank_mask:0xf
	v_add_f32_dpp v133, v133, v133 row_half_mirror row_mask:0xf bank_mask:0xf
	s_nop 0
	s_mov_b32 exec_lo, s100
	s_mov_b32 exec_hi, s100
	global_store_dword v140, v132, s[78:79] offset:2048
	global_store_dword v140, v133, s[78:79] offset:2560
	s_mov_b64 exec, -1
	v_add_u32_e32 v173, 0x10000, v173
	v_add_u32_e32 v177, 0x10000, v177
	v_add_u32_e32 v138, 0x8000, v138
	v_add_u32_e32 v139, 0x8000, v139
	s_waitcnt vmcnt(20)
	v_pk_fma_f32 v[24:25], s[82:83], v[24:25], v[206:207]
	v_pk_fma_f32 v[26:27], s[82:83], v[26:27], v[208:209]
	v_pk_fma_f32 v[8:9], s[82:83], v[8:9], v[210:211]
	v_pk_fma_f32 v[10:11], s[82:83], v[10:11], v[212:213]
	v_pk_fma_f32 v[16:17], s[82:83], v[16:17], v[214:215]
	v_pk_fma_f32 v[18:19], s[82:83], v[18:19], v[216:217]
	v_pk_fma_f32 v[0:1], s[82:83], v[0:1], v[218:219]
	v_pk_fma_f32 v[2:3], s[82:83], v[2:3], v[220:221]
	global_store_dwordx4 v173, v[24:27], s[84:85] nt
	v_cvt_pk_bf16_f32 v164, v24, v25
	v_cvt_pk_bf16_f32 v165, v26, v27
	v_mul_f32_e32 v134, v24, v24
	v_fmac_f32_e32 v134, v25, v25
	v_fmac_f32_e32 v134, v26, v26
	v_fmac_f32_e32 v134, v27, v27
	global_store_dwordx2 v138, v[164:165], s[10:11]
	global_store_dwordx4 v173, v[8:11], s[84:85] offset:512 nt
	v_cvt_pk_bf16_f32 v166, v8, v9
	v_cvt_pk_bf16_f32 v167, v10, v11
	v_fmac_f32_e32 v134, v8, v8
	v_fmac_f32_e32 v134, v9, v9
	v_fmac_f32_e32 v134, v10, v10
	v_fmac_f32_e32 v134, v11, v11
	global_store_dwordx2 v138, v[166:167], s[10:11] offset:256
	global_store_dwordx4 v177, v[16:19], s[84:85] nt
	v_cvt_pk_bf16_f32 v174, v16, v17
	v_cvt_pk_bf16_f32 v175, v18, v19
	v_mul_f32_e32 v135, v16, v16
	v_fmac_f32_e32 v135, v17, v17
	v_fmac_f32_e32 v135, v18, v18
	v_fmac_f32_e32 v135, v19, v19
	global_store_dwordx2 v139, v[174:175], s[10:11]
	global_store_dwordx4 v177, v[0:3], s[84:85] offset:512 nt
	v_cvt_pk_bf16_f32 v142, v0, v1
	v_cvt_pk_bf16_f32 v143, v2, v3
	v_fmac_f32_e32 v135, v0, v0
	v_fmac_f32_e32 v135, v1, v1
	v_fmac_f32_e32 v135, v2, v2
	v_fmac_f32_e32 v135, v3, v3
	global_store_dwordx2 v139, v[142:143], s[10:11] offset:256
	s_nop 1
	v_add_f32_dpp v134, v134, v134 quad_perm:[1,0,3,2] row_mask:0xf bank_mask:0xf
	v_add_f32_dpp v135, v135, v135 quad_perm:[1,0,3,2] row_mask:0xf bank_mask:0xf
	s_nop 0
	v_add_f32_dpp v134, v134, v134 quad_perm:[2,3,0,1] row_mask:0xf bank_mask:0xf
	v_add_f32_dpp v135, v135, v135 quad_perm:[2,3,0,1] row_mask:0xf bank_mask:0xf
	s_nop 0
	v_add_f32_dpp v134, v134, v134 row_half_mirror row_mask:0xf bank_mask:0xf
	v_add_f32_dpp v135, v135, v135 row_half_mirror row_mask:0xf bank_mask:0xf
	s_nop 0
	s_mov_b32 exec_lo, s100
	s_mov_b32 exec_hi, s100
	global_store_dword v140, v134, s[78:79] offset:3072
	global_store_dword v140, v135, s[78:79] offset:3584
	s_mov_b64 exec, -1
	s_branch .LBB0_514

	.amdhsa_kernel _Z10fwd_kernel6Params
		.amdhsa_group_segment_fixed_size 2048
		.amdhsa_private_segment_fixed_size 0
		.amdhsa_kernarg_size 544
		.amdhsa_user_sgpr_count 2
		.amdhsa_user_sgpr_dispatch_ptr 0
		.amdhsa_user_sgpr_queue_ptr 0
		.amdhsa_user_sgpr_kernarg_segment_ptr 1
		.amdhsa_user_sgpr_dispatch_id 0
		.amdhsa_user_sgpr_kernarg_preload_length 0
		.amdhsa_user_sgpr_kernarg_preload_offset 0
		.amdhsa_user_sgpr_private_segment_size 0
		.amdhsa_uses_dynamic_stack 0
		.amdhsa_enable_private_segment 0
		.amdhsa_system_sgpr_workgroup_id_x 1
		.amdhsa_system_sgpr_workgroup_id_y 0
		.amdhsa_system_sgpr_workgroup_id_z 0
		.amdhsa_system_sgpr_workgroup_info 0
		.amdhsa_system_vgpr_workitem_id 2
		.amdhsa_next_free_vgpr 256
		.amdhsa_next_free_sgpr 102
		.amdhsa_accum_offset 256
		.amdhsa_reserve_vcc 1
		.amdhsa_float_round_mode_32 0
		.amdhsa_float_round_mode_16_64 0
		.amdhsa_float_denorm_mode_32 3
		.amdhsa_float_denorm_mode_16_64 3
		.amdhsa_dx10_clamp 1
		.amdhsa_ieee_mode 1
		.amdhsa_fp16_overflow 0
		.amdhsa_tg_split 0
		.amdhsa_exception_fp_ieee_invalid_op 0
		.amdhsa_exception_fp_denorm_src 0
		.amdhsa_exception_fp_ieee_div_zero 0
		.amdhsa_exception_fp_ieee_overflow 0
		.amdhsa_exception_fp_ieee_underflow 0
		.amdhsa_exception_fp_ieee_inexact 0
		.amdhsa_exception_int_div_zero 0
	.end_amdhsa_kernel

amdhsa.kernels:
  - .agpr_count:     0
    .args:
      - .offset:         0
        .size:           288
        .value_kind:     by_value
      - .offset:         288
        .size:           4
        .value_kind:     hidden_block_count_x
      - .offset:         292
        .size:           4
        .value_kind:     hidden_block_count_y
      - .offset:         296
        .size:           4
        .value_kind:     hidden_block_count_z
      - .offset:         300
        .size:           2
        .value_kind:     hidden_group_size_x
      - .offset:         302
        .size:           2
        .value_kind:     hidden_group_size_y
      - .offset:         304
        .size:           2
        .value_kind:     hidden_group_size_z
      - .offset:         306
        .size:           2
        .value_kind:     hidden_remainder_x
      - .offset:         308
        .size:           2
        .value_kind:     hidden_remainder_y
      - .offset:         310
        .size:           2
        .value_kind:     hidden_remainder_z
      - .offset:         328
        .size:           8
        .value_kind:     hidden_global_offset_x
      - .offset:         336
        .size:           8
        .value_kind:     hidden_global_offset_y
      - .offset:         344
        .size:           8
        .value_kind:     hidden_global_offset_z
      - .offset:         352
        .size:           2
        .value_kind:     hidden_grid_dims
      - .offset:         376
        .size:           8
        .value_kind:     hidden_multigrid_sync_arg
      - .offset:         408
        .size:           4
        .value_kind:     hidden_dynamic_lds_size
    .group_segment_fixed_size: 2048
    .kernarg_segment_align: 8
    .kernarg_segment_size: 544
    .language:       OpenCL C
    .language_version:
      - 2
      - 0
    .max_flat_workgroup_size: 512
    .name:           _Z10fwd_kernel6Params
    .private_segment_fixed_size: 0
    .sgpr_count:     108
    .sgpr_spill_count: 83
    .symbol:         _Z10fwd_kernel6Params.kd
    .uniform_work_group_size: 1
    .uses_dynamic_stack: false
    .vgpr_count:     256
    .vgpr_spill_count: 0
    .wavefront_size: 64
